# grid barrier: non-leader workgroups wait on the chip-wide generation word directly; the XCD leader no longer republishes a per-XCD generation nor waits for its own increments
# speedup vs baseline: 1.0072x; 1.0015x over previous
; #define LAS __attribute__((address_space(3)))
; __device__ __forceinline__ unsigned xb_ld(unsigned* p)              { return __hip_atomic_load(p, __ATOMIC_RELAXED, __HIP_MEMORY_SCOPE_AGENT); }
; __device__ __forceinline__ void xcd_barrier_complete(unsigned* bar, unsigned x, unsigned& nloc, unsigned& nx) {
;     const unsigned G = gridDim.x * gridDim.y * gridDim.z;
;     unsigned sum, cnt, mine, sp = 0u;
;     for (;;) {
;         sum = 0u; cnt = 0u; mine = 0u;
; #pragma unroll
;         for (unsigned j = 0; j < 16; ++j) { const unsigned c = xb_ld(&bar[XB_XCNT(j)]); sum += c; cnt += (c > 0u) ? 1u : 0u; mine = (j == x) ? c : mine; }
; __global__ void __launch_bounds__(512, 2) mega(Params P, int ph_lo, int ph_hi) {
;     extern __shared__ __attribute__((aligned(16))) unsigned char smem[];
;     LAS unsigned char* lds = (LAS unsigned char*)smem;
;     if (ph_lo > ph_hi) cg::this_grid().sync();
;     volatile LAS unsigned* st = (volatile LAS unsigned*)(lds + 131072);
;     if (threadIdx.x < 2) st[threadIdx.x] = 0u;
;     __syncthreads();
;     const XcdBarrier bar = xcd_barrier_post((unsigned*)(P.ws + O_BAR), st);
;     for (int ph = ph_lo; ph < ph_hi; ++ph) {
;         if (ph > ph_lo) xcd_barrier(bar);
;         run_phase(fresh_params(), ph, lds);
.LBB0_20:
	s_or_b64 exec, exec, s[4:5]
	s_cmp_ge_i32 s82, s83
	s_cbranch_scc1 .LBB0_1141
	v_readlane_b32 s4, v254, 1
	v_readlane_b32 s5, v254, 2
	s_add_u32 s50, s4, 0x168
	s_addc_u32 s51, s5, 0
	s_add_u32 s4, s0, 0x27180200
	s_addc_u32 s5, s1, 0
	s_add_u32 s18, s0, 0x27180400
	s_addc_u32 s19, s1, 0
	s_add_u32 s20, s0, 0x27180500
	s_addc_u32 s21, s1, 0
	s_add_u32 s22, s0, 0x27180600
	s_addc_u32 s23, s1, 0
	s_add_u32 s26, s0, 0x27180700
	v_writelane_b32 v254, s4, 5
	s_addc_u32 s27, s1, 0
	s_mov_b32 s95, s82
	v_writelane_b32 v254, s5, 6
	s_add_u32 s4, s0, 0x27180800
	s_addc_u32 s5, s1, 0
	v_writelane_b32 v254, s4, 7
	v_mbcnt_lo_u32_b32 v0, -1, 0
	v_mov_b32_e32 v25, 0
	v_writelane_b32 v254, s5, 8
	s_add_u32 s4, s0, 0x27180900
	s_addc_u32 s5, s1, 0
	v_writelane_b32 v254, s4, 9
	v_mov_b32_e32 v184, 1
	v_mov_b32_e32 v185, 0x358637bd
	v_writelane_b32 v254, s5, 10
	s_add_u32 s4, s0, 0x27180a00
	s_addc_u32 s5, s1, 0
	v_writelane_b32 v254, s4, 11
	v_mov_b32_e32 v186, 11
	v_mbcnt_hi_u32_b32 v187, -1, v0
	v_writelane_b32 v254, s5, 12
	s_add_u32 s4, s0, 0x27180b00
	s_addc_u32 s5, s1, 0
	v_writelane_b32 v254, s4, 13
	v_bfrev_b32_e32 v188, 0.5
	v_mov_b32_e32 v189, 0x900
	v_writelane_b32 v254, s5, 14
	s_add_u32 s4, s0, 0x27180c00
	s_addc_u32 s5, s1, 0
	v_writelane_b32 v254, s4, 15
	v_mov_b32_e32 v190, 0x1200
	v_mov_b32_e32 v191, 0x1b00
	v_writelane_b32 v254, s5, 16
	s_add_u32 s4, s0, 0x27180d00
	s_addc_u32 s5, s1, 0
	v_writelane_b32 v254, s4, 17
	v_mov_b32_e32 v192, 0x9000
	v_mov_b32_e32 v193, 0x1800
	v_writelane_b32 v254, s5, 18
	s_add_u32 s4, s0, 0x27180e00
	s_addc_u32 s5, s1, 0
	v_writelane_b32 v254, s4, 19
	v_mov_b32_e32 v194, 0x41b17218
	v_mov_b32_e32 v195, 0x2400
	v_writelane_b32 v254, s5, 20
	s_add_u32 s4, s0, 0x27180f00
	s_addc_u32 s5, s1, 0
	v_writelane_b32 v254, s4, 21
	v_mov_b32_e32 v196, 0x2490
	v_mov_b32_e32 v197, 0x2520
	v_writelane_b32 v254, s5, 22
	s_add_u32 s4, s0, 0x27181000
	s_addc_u32 s5, s1, 0
	v_writelane_b32 v254, s4, 23
	v_mov_b32_e32 v198, 0x25b0
	v_mov_b32_e32 v199, 0x2640
	v_writelane_b32 v254, s5, 24
	s_add_u32 s4, s0, 0x27181100
	s_addc_u32 s5, s1, 0
	v_writelane_b32 v254, s4, 25
	v_mov_b32_e32 v200, 0x26d0
	v_mov_b32_e32 v201, 0x2760
	v_writelane_b32 v254, s5, 26
	s_add_u32 s4, s0, 0x27181200
	s_addc_u32 s5, s1, 0
	v_writelane_b32 v254, s4, 27
	v_mov_b32_e32 v202, 0x27f0
	v_mov_b32_e32 v203, 4
	v_writelane_b32 v254, s5, 28
	s_add_u32 s4, s0, 0x27181300
	s_addc_u32 s5, s1, 0
	v_writelane_b32 v254, s4, 29
	s_cmp_eq_u32 s8, 15
	v_mov_b32_e32 v204, 2
	v_writelane_b32 v254, s5, 30
	s_cselect_b64 s[4:5], -1, 0
	v_writelane_b32 v254, s4, 31
	s_cmp_eq_u32 s8, 14
	v_mov_b32_e32 v205, 6
	v_writelane_b32 v254, s5, 32
	s_cselect_b64 s[4:5], -1, 0
	v_writelane_b32 v254, s4, 33
	s_cmp_eq_u32 s8, 13
	v_mov_b32_e32 v206, 31
	v_writelane_b32 v254, s5, 34
	s_cselect_b64 s[4:5], -1, 0
	v_writelane_b32 v254, s4, 35
	s_cmp_eq_u32 s8, 12
	v_mov_b32_e32 v207, -15
	v_writelane_b32 v254, s5, 36
	s_cselect_b64 s[4:5], -1, 0
	v_writelane_b32 v254, s4, 37
	s_cmp_eq_u32 s8, 11
	v_mov_b32_e32 v208, 0x800000
	v_writelane_b32 v254, s5, 38
	s_cselect_b64 s[4:5], -1, 0
	v_writelane_b32 v254, s4, 39
	s_cmp_eq_u32 s8, 10
	v_mov_b32_e32 v209, 63
	v_writelane_b32 v254, s5, 40
	s_cselect_b64 s[4:5], -1, 0
	v_writelane_b32 v254, s4, 41
	s_cmp_eq_u32 s8, 9
	v_mov_b32_e32 v210, 3
	v_writelane_b32 v254, s5, 42
	s_cselect_b64 s[4:5], -1, 0
	v_writelane_b32 v254, s4, 43
	s_cmp_eq_u32 s8, 8
	v_mov_b32_e32 v211, 0x3ff
	v_writelane_b32 v254, s5, 44
	s_cselect_b64 s[4:5], -1, 0
	v_writelane_b32 v254, s4, 45
	s_cmp_eq_u32 s8, 7
	s_mov_b32 s65, 0x20000
	v_writelane_b32 v254, s5, 46
	s_cselect_b64 s[4:5], -1, 0
	v_writelane_b32 v254, s4, 47
	s_cmp_eq_u32 s8, 6
	s_mov_b32 s33, 0xbfb8aa3b
	v_writelane_b32 v254, s5, 48
	s_cselect_b64 s[4:5], -1, 0
	v_writelane_b32 v254, s4, 49
	s_cmp_eq_u32 s8, 5
	s_movk_i32 s86, 0x1000
	v_writelane_b32 v254, s5, 50
	s_cselect_b64 s[4:5], -1, 0
	v_writelane_b32 v254, s4, 51
	s_cmp_eq_u32 s8, 4
	s_movk_i32 s87, 0x1800
	v_writelane_b32 v254, s5, 52
	s_cselect_b64 s[4:5], -1, 0
	v_writelane_b32 v254, s4, 53
	s_cmp_eq_u32 s8, 3
	s_mov_b32 s90, 0x20a61000
	v_writelane_b32 v254, s5, 54
	s_cselect_b64 s[4:5], -1, 0
	v_writelane_b32 v254, s4, 55
	s_cmp_eq_u32 s8, 2
	s_movk_i32 s91, 0x3000
	v_writelane_b32 v254, s5, 56
	s_cselect_b64 s[4:5], -1, 0
	v_writelane_b32 v254, s4, 57
	s_cmp_eq_u32 s8, 1
	s_mov_b32 s84, 0x800000
	v_writelane_b32 v254, s5, 58
	s_cselect_b64 s[4:5], -1, 0
	v_writelane_b32 v254, s4, 59
	s_cmp_eq_u32 s8, 0
	s_mov_b32 s85, 0x3f317217
	v_writelane_b32 v254, s5, 60
	s_cselect_b64 s[4:5], -1, 0
	v_writelane_b32 v254, s4, 61
	s_mov_b32 s28, 0x7f800000
	s_movk_i32 s92, 0x2000
	v_writelane_b32 v254, s5, 62
	s_lshl_b32 s4, s8, 8
	s_add_u32 s2, s2, s4
	s_addc_u32 s3, s3, 0
	s_add_u32 s4, s2, 0x1400
	s_addc_u32 s5, s3, 0
	s_add_u32 s2, s2, 0x2400
	v_writelane_b32 v254, s4, 63
	s_addc_u32 s3, s3, 0
	s_movk_i32 s93, 0x7f0
	v_writelane_b32 v255, s5, 0
	v_writelane_b32 v255, s2, 1
	s_movk_i32 s24, 0x60
	s_movk_i32 s94, 0x3fff
	v_writelane_b32 v255, s3, 2
	s_add_u32 s2, s0, 0x27183400
	s_addc_u32 s3, s1, 0
	v_writelane_b32 v255, s2, 3
	s_add_u32 s0, s0, 0x27183500
	s_addc_u32 s1, s1, 0
	v_writelane_b32 v255, s3, 4
	v_writelane_b32 v255, s0, 5
	s_mov_b32 s35, 1
	s_mov_b32 s37, 0
	v_writelane_b32 v255, s1, 6
	s_add_i32 s0, 0, 0x20000
	v_writelane_b32 v255, s0, 7
	s_add_i32 s0, 0, 0x20004
	v_writelane_b32 v255, s0, 8
	s_add_i32 s0, 0, 0x16000
	v_writelane_b32 v255, s0, 9
	s_add_i32 s0, 0, 0x11c00
	v_writelane_b32 v255, s0, 10
	s_add_i32 s0, 0, 0x4800
	v_writelane_b32 v255, s0, 11
	s_add_i32 s0, 0, 0x3600
	v_writelane_b32 v255, s0, 12
	s_mov_b32 s0, 0
	s_nop 0
	v_writelane_b32 v255, s0, 63
	v_writelane_b32 v255, s50, 13
	s_mov_b64 s[96:97], 0x1400
	s_mov_b32 s68, 0x3a800000
	v_writelane_b32 v255, s51, 14
	v_writelane_b32 v255, s82, 15
	s_mov_b64 s[70:71], 0x1000
	s_mov_b64 s[30:31], 0x1800
	v_writelane_b32 v255, s83, 16
	v_writelane_b32 v255, s18, 17
	s_mov_b64 s[80:81], 0x80
	s_nop 0
	v_writelane_b32 v255, s19, 18
	v_writelane_b32 v255, s20, 19
	s_nop 1
	v_writelane_b32 v255, s21, 20
	v_writelane_b32 v255, s22, 21
	s_nop 1
	v_writelane_b32 v255, s23, 22
	v_writelane_b32 v255, s26, 23
	s_nop 1
	v_writelane_b32 v255, s27, 24
	s_branch .LBB0_24

; __device__ __forceinline__ unsigned xb_ld(unsigned* p)              { return __hip_atomic_load(p, __ATOMIC_RELAXED, __HIP_MEMORY_SCOPE_AGENT); }
; __device__ __forceinline__ unsigned xb_add(unsigned* p, unsigned v) { return __hip_atomic_fetch_add(p, v, __ATOMIC_RELAXED, __HIP_MEMORY_SCOPE_AGENT); }
; #define XB_SPIN(cond, bar) do { unsigned _sp = 0; while (cond) { __builtin_amdgcn_s_sleep(1); \
;     if ((++_sp & 255u) == 0u) { if (xb_ld(&(bar)[XB_TMO])) break; if (_sp > XB_SPIN_CAP) { atomicAdd(&(bar)[XB_TMO], 1u); break; } } } } while (0)
; __device__ __forceinline__ void xcd_barrier(const XcdBarrier& b) {
;     ...
;     if (threadIdx.x == 0) {
;         unsigned* bar = b.bar;
;         __builtin_amdgcn_s_waitcnt(0);
;         unsigned nloc = b.st[0], nx = b.st[1];
;         if (nloc == 0u) { xcd_barrier_complete(bar, b.x, nloc, nx); b.st[0] = nloc; b.st[1] = nx; }
;         const unsigned old = xb_add(&bar[XB_XSUB(b.x)], 1u);
;         const unsigned gen = old / nloc;
;         if (old + 1u == (gen + 1u) * nloc) {
;             __builtin_amdgcn_fence(__ATOMIC_RELEASE, "agent");
;             asm volatile("s_waitcnt vmcnt(0)" ::: "memory");
;             const unsigned og = xb_add(&bar[XB_TOP], 1u);
;             const unsigned tg = og / nx;
;             if (og + 1u == (tg + 1u) * nx) xb_add(&bar[XB_TOPGEN], 1u);
;             else XB_SPIN(xb_ld(&bar[XB_TOPGEN]) == tg, bar);
;             __builtin_amdgcn_fence(__ATOMIC_ACQUIRE, "agent");
;             xb_add(&bar[XB_XGEN(b.x)], 1u);
;             asm volatile("s_waitcnt vmcnt(0)" ::: "memory");
;         } else {
;             XB_SPIN(xb_ld(&bar[XB_XGEN(b.x)]) == gen, bar);
.LBB0_41:
	v_readlane_b32 s6, v255, 63
	s_nop 3
	s_add_i32 s7, s6, 1
	s_nop 0
	v_writelane_b32 v255, s7, 63
	s_mov_b64 s[4:5], exec
	v_mbcnt_lo_u32_b32 v1, s4, 0
	v_mbcnt_hi_u32_b32 v1, s5, v1
	v_cmp_eq_u32_e32 vcc, 0, v1
	s_and_saveexec_b64 s[2:3], vcc
	s_cbranch_execz .LBB0_43
	s_bcnt1_i32_b64 s4, s[4:5]
	v_mov_b32_e32 v3, s4
	v_readlane_b32 s4, v254, 63
	v_readlane_b32 s5, v255, 0
	s_nop 4
	global_atomic_add v3, v25, v3, s[4:5] sc0
.LBB0_43:
	s_or_b64 exec, exec, s[2:3]
	v_cvt_f32_u32_e32 v4, v2
	s_waitcnt vmcnt(0)
	v_readfirstlane_b32 s2, v3
	v_sub_u32_e32 v3, 0, v2
	v_rcp_iflag_f32_e32 v4, v4
	v_add_u32_e32 v5, s2, v1
	v_mul_f32_e32 v4, 0x4f7ffffe, v4
	v_cvt_u32_f32_e32 v4, v4
	v_mul_lo_u32 v1, v3, v4
	v_mul_hi_u32 v1, v4, v1
	v_add_u32_e32 v1, v4, v1
	v_mul_hi_u32 v1, v5, v1
	v_mul_lo_u32 v3, v1, v2
	v_sub_u32_e32 v3, v5, v3
	v_add_u32_e32 v4, 1, v1
	v_sub_u32_e32 v6, v3, v2
	v_cmp_ge_u32_e32 vcc, v3, v2
	s_nop 1
	v_cndmask_b32_e32 v1, v1, v4, vcc
	v_cndmask_b32_e32 v3, v3, v6, vcc
	v_add_u32_e32 v4, 1, v1
	v_cmp_ge_u32_e32 vcc, v3, v2
	v_add_u32_e32 v3, 1, v5
	s_nop 0
	v_cndmask_b32_e32 v1, v1, v4, vcc
	v_mul_lo_u32 v4, v2, v1
	v_add_u32_e32 v2, v4, v2
	v_cmp_ne_u32_e32 vcc, v3, v2
	s_and_saveexec_b64 s[2:3], vcc
	s_xor_b64 s[2:3], exec, s[2:3]
	s_cbranch_execz .LBB0_57
	v_readlane_b32 s4, v255, 5
	v_readlane_b32 s5, v255, 6
	v_mov_b32_e32 v1, s6
	s_waitcnt lgkmcnt(0)
	s_nop 3
	global_load_dword v0, v25, s[4:5] sc1
	s_waitcnt vmcnt(0)
	v_cmp_eq_u32_e32 vcc, v0, v1
	s_and_saveexec_b64 s[4:5], vcc
	s_cbranch_execz .LBB0_56
	s_mov_b32 s16, 1
	s_mov_b64 s[6:7], 0
	s_branch .LBB0_47

; __device__ __forceinline__ unsigned xb_ld(unsigned* p)              { return __hip_atomic_load(p, __ATOMIC_RELAXED, __HIP_MEMORY_SCOPE_AGENT); }
; #define XB_SPIN(cond, bar) do { unsigned _sp = 0; while (cond) { __builtin_amdgcn_s_sleep(1); \
;     if ((++_sp & 255u) == 0u) { if (xb_ld(&(bar)[XB_TMO])) break; if (_sp > XB_SPIN_CAP) { atomicAdd(&(bar)[XB_TMO], 1u); break; } } } } while (0)
; __device__ __forceinline__ void xcd_barrier(const XcdBarrier& b) {
;     ...
;             XB_SPIN(xb_ld(&bar[XB_XGEN(b.x)]) == gen, bar);
.LBB0_49:
	v_readlane_b32 s10, v255, 5
	v_readlane_b32 s11, v255, 6
	s_add_i32 s16, s16, 1
	s_mov_b64 s[12:13], -1
	s_nop 2
	global_load_dword v0, v25, s[10:11] sc1
	s_waitcnt vmcnt(0)
	v_cmp_ne_u32_e32 vcc, v0, v1
	s_orn2_b64 s[10:11], vcc, exec
	s_branch .LBB0_46

; __device__ __forceinline__ unsigned xb_ld(unsigned* p)              { return __hip_atomic_load(p, __ATOMIC_RELAXED, __HIP_MEMORY_SCOPE_AGENT); }
; __device__ __forceinline__ unsigned xb_add(unsigned* p, unsigned v) { return __hip_atomic_fetch_add(p, v, __ATOMIC_RELAXED, __HIP_MEMORY_SCOPE_AGENT); }
; #define XB_SPIN(cond, bar) do { unsigned _sp = 0; while (cond) { __builtin_amdgcn_s_sleep(1); \
;     if ((++_sp & 255u) == 0u) { if (xb_ld(&(bar)[XB_TMO])) break; if (_sp > XB_SPIN_CAP) { atomicAdd(&(bar)[XB_TMO], 1u); break; } } } } while (0)
; __device__ __forceinline__ void xcd_barrier(const XcdBarrier& b) {
;     ...
;             __builtin_amdgcn_fence(__ATOMIC_ACQUIRE, "agent");
;             xb_add(&bar[XB_XGEN(b.x)], 1u);
;             asm volatile("s_waitcnt vmcnt(0)" ::: "memory");
;         } else {
;             XB_SPIN(xb_ld(&bar[XB_XGEN(b.x)]) == gen, bar);
;             __builtin_amdgcn_fence(__ATOMIC_ACQUIRE, "agent");
;             asm volatile("s_waitcnt vmcnt(0)" ::: "memory");
;         }
;     }
;     __syncthreads();
.LBB0_74:
	s_or_b64 exec, exec, s[2:3]
	s_mov_b64 s[2:3], exec
	v_mbcnt_lo_u32_b32 v0, s2, 0
	v_mbcnt_hi_u32_b32 v0, s3, v0
	v_cmp_eq_u32_e32 vcc, 0, v0
	buffer_inv sc1
.LBB0_76:
.LBB0_77:
	s_or_b64 exec, exec, s[0:1]
	s_waitcnt lgkmcnt(0)
	s_barrier
